# attention QK K-fragment ds_reads pipelined (11 in flight) + first phase seam uses XCD barrier instead of cg grid sync
# speedup vs baseline: 1.0412x; 1.0068x over previous
.LBB0_842:
	s_mul_i32 s22, s19, 0x3000
	v_add_u32_e32 v156, s22, v183
	ds_read_b128 v[112:115], v156
	ds_read_b128 v[152:155], v156 offset:512
	ds_read_b128 v[206:209], v156 offset:2048
	ds_read_b128 v[210:213], v156 offset:2560
	ds_read_b128 v[214:217], v156 offset:4096
	ds_read_b128 v[218:221], v156 offset:4608
	ds_read_b128 v[222:225], v156 offset:6144
	ds_read_b128 v[226:229], v156 offset:6656
	ds_read_b128 v[236:239], v156 offset:8192
	ds_read_b128 v[240:243], v156 offset:8704
	ds_read_b128 v[248:251], v156 offset:10240
	s_waitcnt lgkmcnt(10)
	v_mfma_f32_32x32x16_bf16 v[96:111], v[112:115], v[128:131], v[80:95]
	s_waitcnt lgkmcnt(9)
	v_mfma_f32_32x32x16_bf16 v[112:127], v[152:155], v[128:131], v[80:95]
	ds_read_b128 v[152:155], v156 offset:10752
	s_waitcnt lgkmcnt(9)
	v_mfma_f32_32x32x16_bf16 v[96:111], v[206:209], v[132:135], v[96:111]
	s_waitcnt lgkmcnt(8)
	v_mfma_f32_32x32x16_bf16 v[112:127], v[210:213], v[132:135], v[112:127]
	s_waitcnt lgkmcnt(7)
	v_mfma_f32_32x32x16_bf16 v[96:111], v[214:217], v[136:139], v[96:111]
	s_waitcnt lgkmcnt(6)
	v_mfma_f32_32x32x16_bf16 v[112:127], v[218:221], v[136:139], v[112:127]
	s_waitcnt lgkmcnt(5)
	v_mfma_f32_32x32x16_bf16 v[96:111], v[222:225], v[140:143], v[96:111]
	s_waitcnt lgkmcnt(4)
	v_mfma_f32_32x32x16_bf16 v[112:127], v[226:229], v[140:143], v[112:127]
	s_waitcnt lgkmcnt(3)
	v_mfma_f32_32x32x16_bf16 v[96:111], v[236:239], v[144:147], v[96:111]
	s_waitcnt lgkmcnt(2)
	v_mfma_f32_32x32x16_bf16 v[112:127], v[240:243], v[144:147], v[112:127]
	s_waitcnt lgkmcnt(1)
	v_mfma_f32_32x32x16_bf16 v[96:111], v[248:251], v[148:151], v[96:111]
	s_waitcnt lgkmcnt(0)
	v_mfma_f32_32x32x16_bf16 v[112:127], v[152:155], v[148:151], v[112:127]
	s_or_b64 exec, exec, s[16:17]
	s_cmp_gt_i32 s1, s72
	s_cbranch_scc1 .LBB0_838

.LBB0_860:
	v_add_u32_e32 v156, s21, v183
	ds_read_b128 v[64:67], v156
	ds_read_b128 v[152:155], v156 offset:512
	ds_read_b128 v[206:209], v156 offset:2048
	ds_read_b128 v[210:213], v156 offset:2560
	ds_read_b128 v[214:217], v156 offset:4096
	ds_read_b128 v[218:221], v156 offset:4608
	ds_read_b128 v[222:225], v156 offset:6144
	ds_read_b128 v[226:229], v156 offset:6656
	ds_read_b128 v[236:239], v156 offset:8192
	ds_read_b128 v[240:243], v156 offset:8704
	ds_read_b128 v[248:251], v156 offset:10240
	s_waitcnt lgkmcnt(10)
	v_mfma_f32_32x32x16_bf16 v[48:63], v[64:67], v[128:131], v[80:95]
	s_waitcnt lgkmcnt(9)
	v_mfma_f32_32x32x16_bf16 v[64:79], v[152:155], v[128:131], v[80:95]
	ds_read_b128 v[152:155], v156 offset:10752
	s_waitcnt lgkmcnt(9)
	v_mfma_f32_32x32x16_bf16 v[48:63], v[206:209], v[132:135], v[48:63]
	s_waitcnt lgkmcnt(8)
	v_mfma_f32_32x32x16_bf16 v[64:79], v[210:213], v[132:135], v[64:79]
	s_waitcnt lgkmcnt(7)
	v_mfma_f32_32x32x16_bf16 v[48:63], v[214:217], v[136:139], v[48:63]
	s_waitcnt lgkmcnt(6)
	v_mfma_f32_32x32x16_bf16 v[64:79], v[218:221], v[136:139], v[64:79]
	s_waitcnt lgkmcnt(5)
	v_mfma_f32_32x32x16_bf16 v[48:63], v[222:225], v[140:143], v[48:63]
	s_waitcnt lgkmcnt(4)
	v_mfma_f32_32x32x16_bf16 v[64:79], v[226:229], v[140:143], v[64:79]
	s_waitcnt lgkmcnt(3)
	v_mfma_f32_32x32x16_bf16 v[48:63], v[236:239], v[144:147], v[48:63]
	s_waitcnt lgkmcnt(2)
	v_mfma_f32_32x32x16_bf16 v[64:79], v[240:243], v[144:147], v[64:79]
	s_waitcnt lgkmcnt(1)
	v_mfma_f32_32x32x16_bf16 v[48:63], v[248:251], v[148:151], v[48:63]
	s_waitcnt lgkmcnt(0)
	v_mfma_f32_32x32x16_bf16 v[64:79], v[152:155], v[148:151], v[64:79]
	s_and_saveexec_b64 s[14:15], s[2:3]
	s_cbranch_execz .LBB0_870

.LBB0_2018:
	v_readlane_b32 s0, v255, 4
	v_readlane_b32 s2, v255, 6
	v_readlane_b32 s3, v255, 7
	s_cmp_lg_u32 s29, s0
	s_mov_b64 s[2:3], -1
	v_readlane_b32 s1, v255, 5
	s_getreg_b32 s0, hwreg(HW_REG_XCC_ID, 0, 4)
	s_waitcnt vmcnt(0)
	s_waitcnt vmcnt(63) expcnt(7) lgkmcnt(15)
	s_barrier
	s_mov_b64 s[6:7], exec
	v_readlane_b32 s2, v255, 32
	v_readlane_b32 s3, v255, 33
	s_and_b64 s[2:3], s[6:7], s[2:3]
	s_mov_b64 exec, s[2:3]
	s_cbranch_execz .LBB0_2071
	s_mov_b32 s2, 0
	s_ashr_i32 s3, s2, 31
	v_readlane_b32 s8, v255, 27
	s_and_b32 s0, s0, 15
	s_lshl_b64 s[2:3], s[2:3], 2
	v_readlane_b32 s10, v255, 29
	v_readlane_b32 s11, v255, 30
	s_add_u32 s2, s10, s2
	s_addc_u32 s3, s11, s3
	s_add_i32 s24, 16, 0x26800
	v_readlane_b32 s9, v255, 28
	s_cmp_lg_u32 s24, -1
	s_cselect_b32 s1, s24, 0
	s_mov_b64 s[8:9], src_shared_base
	s_cselect_b32 s8, s9, 0
	v_mov_b32_e32 v0, s1
	s_add_i32 s1, 16, 0x26804
	s_cmp_lg_u32 s1, -1
	v_mov_b32_e32 v1, s8
	s_cselect_b32 s8, s1, 0
	s_cselect_b32 s9, s9, 0
	s_waitcnt vmcnt(0) expcnt(0) lgkmcnt(0)
	flat_load_dword v2, v[0:1] sc0 sc1
	s_waitcnt vmcnt(0)
	v_mov_b32_e32 v0, s8
	v_mov_b32_e32 v1, s9
	flat_load_dword v0, v[0:1] sc0 sc1
	s_waitcnt vmcnt(0) lgkmcnt(0)
	v_cmp_eq_u32_e32 vcc, 0, v2
	s_and_saveexec_b64 s[8:9], vcc
	s_cbranch_execz .LBB0_2035
	s_add_u32 s10, s2, 0x1000
	s_addc_u32 s11, s3, 0
	s_add_u32 s12, s2, 0x1100
	s_addc_u32 s13, s3, 0
	s_add_u32 s14, s2, 0x1200
	s_addc_u32 s15, s3, 0
	s_add_u32 s16, s2, 0x1300
	s_addc_u32 s17, s3, 0
	s_mov_b32 s25, 1
	s_branch .LBB0_2023
